# first phase seam uses the XCD-hierarchical barrier instead of cooperative-groups grid sync; unreachable cg sync code deleted
# speedup vs baseline: 1.0118x; 1.0118x over previous
.LBB0_5:
	s_or_b64 exec, exec, s[6:7]
	s_load_dwordx2 s[6:7], s[78:79], 0xd0
	s_waitcnt lgkmcnt(0)
	v_writelane_b32 v254, s6, 3
	s_nop 1
	v_writelane_b32 v254, s7, 4
	s_cmp_ge_i32 s6, s7
	s_cbranch_scc1 .LBB0_1209
	s_add_u32 s74, s78, 0xd8
	s_addc_u32 s75, s79, 0
	s_cmp_lg_u32 0, -1
	s_cselect_b64 s[6:7], -1, 0
	v_writelane_b32 v254, s6, 5
	v_lshrrev_b32_e32 v1, 20, v0
	v_lshrrev_b32_e32 v0, 10, v0
	v_writelane_b32 v254, s7, 6
	v_or_b32_e32 v0, v0, v1
	v_readlane_b32 s6, v254, 0
	s_ashr_i32 s3, s6, 31
	v_writelane_b32 v254, s3, 7
	s_lshr_b32 s3, s3, 29
	s_add_i32 s3, s6, s3
	s_ashr_i32 s7, s3, 3
	s_and_b32 s3, s3, -8
	v_writelane_b32 v254, s7, 8
	s_sub_i32 s3, s6, s3
	v_writelane_b32 v254, s3, 9
	s_lshr_b32 s3, s3, 31
	s_add_u32 s6, s0, 0x13c56400
	v_writelane_b32 v254, s3, 10
	s_addc_u32 s7, s1, 0
	v_writelane_b32 v254, s6, 11
	v_mov_b32_e32 v173, 0
	v_mov_b64_e32 v[174:175], 0x800
	v_writelane_b32 v254, s7, 12
	s_add_u32 s6, s0, 0x13c56600
	s_addc_u32 s7, s1, 0
	v_writelane_b32 v254, s6, 13
	v_mov_b32_e32 v176, 0x358637bd
	v_mov_b32_e32 v191, 0x3ecc95a3
	v_writelane_b32 v254, s7, 14
	s_add_u32 s6, s0, 0x13c56700
	s_addc_u32 s7, s1, 0
	v_writelane_b32 v254, s6, 15
	v_mov_b32_e32 v193, 0x3c0881c4
	v_mov_b32_e32 v195, 0xbab64f3b
	v_writelane_b32 v254, s7, 16
	s_add_u32 s6, s0, 0x13c56800
	s_addc_u32 s7, s1, 0
	v_writelane_b32 v254, s6, 17
	v_bfrev_b32_e32 v223, 0.5
	v_mov_b32_e32 v224, 0xf149f2ca
	v_writelane_b32 v254, s7, 18
	s_add_u32 s6, s0, 0x13c56900
	s_addc_u32 s7, s1, 0
	v_writelane_b32 v254, s6, 19
	v_mov_b32_e32 v226, 0x182
	v_mov_b32_e32 v178, 0x3f317218
	v_writelane_b32 v254, s7, 20
	s_add_u32 s6, s0, 0x13c56a00
	s_addc_u32 s7, s1, 0
	v_writelane_b32 v254, s6, 21
	v_mov_b32_e32 v227, 0x7f800000
	v_mov_b32_e32 v228, 0x7fc00000
	v_writelane_b32 v254, s7, 22
	s_add_u32 s6, s0, 0x13c56b00
	s_addc_u32 s7, s1, 0
	v_writelane_b32 v254, s6, 23
	v_mov_b32_e32 v229, 0xff800000
	v_mov_b64_e32 v[180:181], 0x13c10200
	v_writelane_b32 v254, s7, 24
	s_add_u32 s6, s0, 0x13c56c00
	s_addc_u32 s7, s1, 0
	v_writelane_b32 v254, s6, 25
	v_mov_b32_e32 v225, 0x40000
	v_not_b32_e32 v222, 63
	v_writelane_b32 v254, s7, 26
	s_add_u32 s6, s0, 0x13c56d00
	s_addc_u32 s7, s1, 0
	v_writelane_b32 v254, s6, 27
	v_not_b32_e32 v232, 31
	s_movk_i32 s97, 0x80
	v_writelane_b32 v254, s7, 28
	s_add_u32 s6, s0, 0x13c56e00
	s_addc_u32 s7, s1, 0
	v_writelane_b32 v254, s6, 29
	s_movk_i32 s73, 0x1000
	s_mov_b32 s88, 0x800000
	v_writelane_b32 v254, s7, 30
	s_add_u32 s6, s0, 0x13c56f00
	s_addc_u32 s7, s1, 0
	v_writelane_b32 v254, s6, 31
	s_movk_i32 s89, 0x110
	s_movk_i32 s21, 0x183
	v_writelane_b32 v254, s7, 32
	s_add_u32 s6, s0, 0x13c57000
	s_addc_u32 s7, s1, 0
	v_writelane_b32 v254, s6, 33
	s_mov_b32 s13, 0xfe03f81
	s_movk_i32 s16, 0xff7f
	v_writelane_b32 v254, s7, 34
	s_add_u32 s6, s0, 0x13c57100
	s_addc_u32 s7, s1, 0
	v_writelane_b32 v254, s6, 35
	s_movk_i32 s18, 0x81
	s_movk_i32 s14, 0x100
	v_writelane_b32 v254, s7, 36
	s_add_u32 s6, s0, 0x13c57200
	s_addc_u32 s7, s1, 0
	v_writelane_b32 v254, s6, 37
	s_movk_i32 s37, 0x5200
	s_mov_b32 s90, 0x41a00000
	v_writelane_b32 v254, s7, 38
	s_add_u32 s6, s0, 0x13c57300
	s_addc_u32 s7, s1, 0
	v_writelane_b32 v254, s6, 39
	s_movk_i32 s23, 0x6000
	s_mov_b32 s19, 0xc000
	v_writelane_b32 v254, s7, 40
	s_add_u32 s6, s0, 0x13c57400
	s_addc_u32 s7, s1, 0
	v_writelane_b32 v254, s6, 41
	s_mov_b32 s33, 0x12000
	s_mov_b32 s22, 0x5040100
	v_writelane_b32 v254, s7, 42
	s_add_u32 s6, s0, 0x13c57500
	s_addc_u32 s7, s1, 0
	v_writelane_b32 v254, s6, 43
	s_cmp_eq_u32 s2, 15
	s_mov_b32 s36, 0x1e579000
	v_writelane_b32 v254, s7, 44
	s_cselect_b64 s[6:7], -1, 0
	v_writelane_b32 v254, s6, 45
	s_cmp_eq_u32 s2, 14
	s_mov_b32 s12, 0x22579000
	v_writelane_b32 v254, s7, 46
	s_cselect_b64 s[6:7], -1, 0
	v_writelane_b32 v254, s6, 47
	s_cmp_eq_u32 s2, 13
	s_mov_b32 s31, 0
	v_writelane_b32 v254, s7, 48
	s_cselect_b64 s[6:7], -1, 0
	v_writelane_b32 v254, s6, 49
	s_cmp_eq_u32 s2, 12
	s_mov_b64 s[34:35], 0x800
	v_writelane_b32 v254, s7, 50
	s_cselect_b64 s[6:7], -1, 0
	v_writelane_b32 v254, s6, 51
	s_cmp_eq_u32 s2, 11
	s_mov_b64 s[38:39], 0x800000
	v_writelane_b32 v254, s7, 52
	s_cselect_b64 s[6:7], -1, 0
	v_writelane_b32 v254, s6, 53
	s_cmp_eq_u32 s2, 10
	s_mov_b64 s[54:55], 0x80
	v_writelane_b32 v254, s7, 54
	s_cselect_b64 s[6:7], -1, 0
	v_writelane_b32 v254, s6, 55
	s_cmp_eq_u32 s2, 9
	s_nop 0
	v_writelane_b32 v254, s7, 56
	s_cselect_b64 s[6:7], -1, 0
	v_writelane_b32 v254, s6, 57
	s_cmp_eq_u32 s2, 8
	s_nop 0
	v_writelane_b32 v254, s7, 58
	s_cselect_b64 s[6:7], -1, 0
	v_writelane_b32 v254, s6, 59
	s_cmp_eq_u32 s2, 7
	s_nop 0
	v_writelane_b32 v254, s7, 60
	s_cselect_b64 s[6:7], -1, 0
	v_writelane_b32 v254, s6, 61
	s_cmp_eq_u32 s2, 6
	s_nop 0
	v_writelane_b32 v254, s7, 62
	s_cselect_b64 s[6:7], -1, 0
	v_writelane_b32 v254, s6, 63
	s_cmp_eq_u32 s2, 5
	s_nop 0
	v_writelane_b32 v255, s7, 0
	s_cselect_b64 s[6:7], -1, 0
	v_writelane_b32 v255, s6, 1
	s_cmp_eq_u32 s2, 4
	s_nop 0
	v_writelane_b32 v255, s7, 2
	s_cselect_b64 s[6:7], -1, 0
	v_writelane_b32 v255, s6, 3
	s_cmp_eq_u32 s2, 3
	s_nop 0
	v_writelane_b32 v255, s7, 4
	s_cselect_b64 s[6:7], -1, 0
	v_writelane_b32 v255, s6, 5
	s_cmp_eq_u32 s2, 2
	s_nop 0
	v_writelane_b32 v255, s7, 6
	s_cselect_b64 s[6:7], -1, 0
	v_writelane_b32 v255, s6, 7
	s_cmp_eq_u32 s2, 1
	s_nop 0
	v_writelane_b32 v255, s7, 8
	s_cselect_b64 s[6:7], -1, 0
	v_writelane_b32 v255, s6, 9
	s_cmp_eq_u32 s2, 0
	s_nop 0
	v_writelane_b32 v255, s7, 10
	s_cselect_b64 s[6:7], -1, 0
	s_lshl_b32 s2, s2, 8
	s_add_u32 s2, s4, s2
	s_addc_u32 s3, s5, 0
	v_writelane_b32 v255, s6, 11
	s_add_u32 s4, s2, 0x1400
	s_addc_u32 s5, s3, 0
	v_writelane_b32 v255, s7, 12
	v_writelane_b32 v255, s4, 13
	s_add_u32 s2, s2, 0x2400
	s_addc_u32 s3, s3, 0
	v_writelane_b32 v255, s5, 14
	v_writelane_b32 v255, s2, 15
	s_nop 1
	v_writelane_b32 v255, s3, 16
	s_add_u32 s2, s0, 0x13c59600
	s_addc_u32 s3, s1, 0
	v_writelane_b32 v255, s2, 17
	s_add_u32 s0, s0, 0x13c59700
	s_addc_u32 s1, s1, 0
	v_writelane_b32 v255, s3, 18
	v_writelane_b32 v255, s0, 19
	s_add_i32 s3, 0, 0x14000
	s_nop 0
	v_writelane_b32 v255, s1, 20
	s_movk_i32 s0, 0x3ff
	v_and_or_b32 v0, v0, s0, v177
	s_add_i32 s0, 0, 0x13000
	v_writelane_b32 v255, s0, 21
	s_add_i32 s0, 0, 0xa800
	v_writelane_b32 v255, s0, 22
	s_add_i32 s0, 0, 0x20004
	v_writelane_b32 v255, s0, 23
	s_load_dwordx2 s[0:1], s[78:79], 0xd0
	s_waitcnt lgkmcnt(0)
	s_mov_b32 s10, s0
	v_cmp_eq_u32_e64 s[0:1], 0, v0
	s_nop 1
	v_writelane_b32 v255, s0, 24
	s_nop 1
	v_writelane_b32 v255, s1, 25
	v_writelane_b32 v255, s78, 26
	s_nop 1
	v_writelane_b32 v255, s79, 27
	v_writelane_b32 v255, s74, 28
	s_nop 1
	v_writelane_b32 v255, s75, 29
	s_branch .LBB0_11
.LBB0_9:
	s_mov_b64 s[0:1], 0

.LBB0_1141:
	v_readlane_b32 s0, v254, 3
	s_add_i32 s10, s30, 1
	v_readlane_b32 s1, v254, 4
	s_cmp_ge_i32 s10, s1
	s_mov_b64 s[0:1], -1
	s_cbranch_scc1 .LBB0_10
	s_waitcnt vmcnt(0)
	s_barrier
	s_mov_b64 s[0:1], exec
	v_readlane_b32 s4, v254, 1
	v_readlane_b32 s5, v254, 2
	s_and_b64 s[4:5], s[0:1], s[4:5]
	s_mov_b64 exec, s[4:5]
	s_cbranch_execz .LBB0_1198
	s_add_i32 s2, 0, 0x20000
	s_waitcnt vmcnt(1)
	v_mov_b32_e32 v0, s2
	s_waitcnt vmcnt(0) expcnt(0) lgkmcnt(0)
	ds_read_b32 v2, v0
	v_readlane_b32 s4, v255, 23
	s_waitcnt lgkmcnt(0)
	v_cmp_ne_u32_e32 vcc, 0, v2
	v_mov_b32_e32 v0, s4
	ds_read_b32 v0, v0
	s_cbranch_vccnz .LBB0_1161
	s_load_dwordx2 s[4:5], s[74:75], 0x4
	s_mov_b32 s15, 1
	s_waitcnt lgkmcnt(0)
	s_mul_i32 s11, s4, s50
	s_mul_i32 s11, s11, s5
	s_branch .LBB0_1147

.LBB0_1198:
	s_or_b64 exec, exec, s[0:1]
	s_mov_b64 s[0:1], 0
	s_waitcnt lgkmcnt(0)
	s_barrier
.LBB0_1199:
	s_branch .LBB0_9
.LBB0_1209:
	s_endpgm
